# gla_wave_a tiles fetched with row-coalesced loads and staged through LDS; sample attention spread over 64 WGs
# speedup vs baseline: 1.0044x; 1.0023x over previous
.LBB0_699:
	s_add_i32 s38, s21, s95
	v_readlane_b32 s50, v244, 38
	s_cmpk_gt_i32 s38, 0x7ff
	v_readlane_b32 s51, v244, 39
	s_barrier
	s_cbranch_scc1 .LBB0_704
	s_mulk_i32 s21, 0x4400
	s_add_i32 s10, s21, 0
	s_add_u32 s42, s0, 0x1cc00000
	s_addc_u32 s43, s1, 0
	s_add_u32 s44, s0, 0x1ec80000
	v_mov_b32_e32 v65, 0
	v_lshlrev_b32_e32 v64, 2, v162
	s_addc_u32 s45, s1, 0
	v_lshl_add_u64 v[0:1], s[0:1], 0, v[64:65]
	s_mov_b64 s[8:9], 0xf800000
	s_add_u32 s21, s0, 0x3600000
	v_lshl_add_u64 v[68:69], v[0:1], 0, s[8:9]
	s_addc_u32 s33, s1, 0
	s_lshr_b32 s8, s20, 6
	v_lshlrev_b32_e32 v3, 15, v224
	s_mov_b32 s9, 0x18b00040
	s_ashr_i32 s39, s38, 31
	v_mul_u32_u24_e32 v0, 0x90, v162
	v_add_u32_e32 v1, s10, v225
	v_add_u32_e32 v2, s10, v226
	v_or3_b32 v64, v3, v163, s9
	s_add_i32 s20, s95, s8
	s_lshl_b64 s[8:9], s[38:39], 15
	v_lshlrev_b32_e32 v3, 10, v222
	s_ashr_i32 s93, s92, 31
	s_mov_b32 s41, 0
	v_lshlrev_b32_e32 v66, 14, v162
	v_or3_b32 v70, s8, v3, v223
	v_mov_b32_e32 v71, s9
	s_lshl_b64 s[46:47], s[92:93], 15
	v_lshlrev_b32_e32 v72, 2, v162
	v_mov_b32_e32 v73, v65
	v_add_u32_e32 v67, s10, v0
	v_add_u32_e32 v78, v1, v163
	v_add_u32_e32 v79, v2, v163
	v_lshrrev_b32_e32 v214, 3, v162
	v_and_b32_e32 v215, 7, v162
	v_lshlrev_b32_e32 v142, 15, v214
	v_lshl_or_b32 v142, v215, 4, v142
	v_mul_u32_u24_e32 v160, 0x90, v214
	v_lshl_add_u32 v160, v215, 4, v160
	v_add_u32_e32 v160, s10, v160
	v_lshrrev_b32_e32 v214, 4, v162
	v_and_b32_e32 v215, 15, v162
	v_lshlrev_b32_e32 v143, 16, v214
	v_lshl_or_b32 v143, v215, 4, v143
	v_mul_u32_u24_e32 v161, 0x110, v214
	v_lshl_add_u32 v161, v215, 4, v161
	v_add_u32_e32 v161, s10, v161
	v_mul_u32_u24_e32 v164, 0x110, v162
	v_add_u32_e32 v164, s10, v164
	v_and_b32_e32 v214, 31, v162
	v_lshrrev_b32_e32 v215, 5, v162
	v_mul_u32_u24_e32 v165, 0x90, v214
	v_lshl_add_u32 v165, v215, 4, v165
	v_add_u32_e32 v165, s10, v165
	v_add_u32_e32 v165, 0x2400, v165
.LBB0_701:
	s_and_b32 s8, s20, 0xff
	s_lshl_b32 s22, s8, 7
	s_ashr_i32 s8, s38, 8
	s_ashr_i32 s9, s8, 31
	s_lshl_b64 s[48:49], s[8:9], 20
	s_and_b32 s23, s38, 0xff
	s_lshl_b64 s[10:11], s[48:49], 2
	s_add_u32 s98, s42, s10
	s_addc_u32 s99, s43, s11
	s_lshl_b32 s40, s23, 8
	s_add_u32 s98, s98, s40
	s_addc_u32 s99, s99, 0
	global_load_dwordx4 v[32:35], v143, s[98:99]
	s_add_u32 s98, s98, 0x40000
	s_addc_u32 s99, s99, 0
	global_load_dwordx4 v[44:47], v143, s[98:99]
	s_add_u32 s98, s98, 0x40000
	s_addc_u32 s99, s99, 0
	global_load_dwordx4 v[40:43], v143, s[98:99]
	s_add_u32 s98, s98, 0x40000
	s_addc_u32 s99, s99, 0
	global_load_dwordx4 v[36:39], v143, s[98:99]
	s_add_u32 s98, s98, 0x40000
	s_addc_u32 s99, s99, 0
	global_load_dwordx4 v[60:63], v143, s[98:99]
	s_add_u32 s98, s98, 0x40000
	s_addc_u32 s99, s99, 0
	global_load_dwordx4 v[56:59], v143, s[98:99]
	s_add_u32 s98, s98, 0x40000
	s_addc_u32 s99, s99, 0
	global_load_dwordx4 v[52:55], v143, s[98:99]
	s_add_u32 s98, s98, 0x40000
	s_addc_u32 s99, s99, 0
	global_load_dwordx4 v[48:51], v143, s[98:99]
	s_add_u32 s98, s98, 0x40000
	s_addc_u32 s99, s99, 0
	global_load_dwordx4 v[122:125], v143, s[98:99]
	s_add_u32 s98, s98, 0x40000
	s_addc_u32 s99, s99, 0
	global_load_dwordx4 v[118:121], v143, s[98:99]
	s_add_u32 s98, s98, 0x40000
	s_addc_u32 s99, s99, 0
	global_load_dwordx4 v[114:117], v143, s[98:99]
	s_add_u32 s98, s98, 0x40000
	s_addc_u32 s99, s99, 0
	global_load_dwordx4 v[110:113], v143, s[98:99]
	s_add_u32 s98, s98, 0x40000
	s_addc_u32 s99, s99, 0
	global_load_dwordx4 v[138:141], v143, s[98:99]
	s_add_u32 s98, s98, 0x40000
	s_addc_u32 s99, s99, 0
	global_load_dwordx4 v[134:137], v143, s[98:99]
	s_add_u32 s98, s98, 0x40000
	s_addc_u32 s99, s99, 0
	global_load_dwordx4 v[130:133], v143, s[98:99]
	s_add_u32 s98, s98, 0x40000
	s_addc_u32 s99, s99, 0
	global_load_dwordx4 v[126:129], v143, s[98:99]
	s_lshl_b64 s[10:11], s[48:49], 1
	s_add_u32 s98, s44, s10
	s_addc_u32 s99, s45, s11
	s_lshl_b32 s40, s23, 7
	s_add_u32 s98, s98, s40
	s_addc_u32 s99, s99, 0
	global_load_dwordx4 v[28:31], v142, s[98:99]
	s_add_u32 s98, s98, 0x40000
	s_addc_u32 s99, s99, 0
	global_load_dwordx4 v[24:27], v142, s[98:99]
	s_add_u32 s98, s98, 0x40000
	s_addc_u32 s99, s99, 0
	global_load_dwordx4 v[20:23], v142, s[98:99]
	s_add_u32 s98, s98, 0x40000
	s_addc_u32 s99, s99, 0
	global_load_dwordx4 v[16:19], v142, s[98:99]
	s_add_u32 s98, s98, 0x40000
	s_addc_u32 s99, s99, 0
	global_load_dwordx4 v[12:15], v142, s[98:99]
	s_add_u32 s98, s98, 0x40000
	s_addc_u32 s99, s99, 0
	global_load_dwordx4 v[8:11], v142, s[98:99]
	s_add_u32 s98, s98, 0x40000
	s_addc_u32 s99, s99, 0
	global_load_dwordx4 v[4:7], v142, s[98:99]
	s_add_u32 s98, s98, 0x40000
	s_addc_u32 s99, s99, 0
	global_load_dwordx4 v[0:3], v142, s[98:99]
	s_ashr_i32 s100, s38, 8
	s_ashr_i32 s101, s100, 31
	s_lshl_b64 s[100:101], s[100:101], 22
	s_or_b32 s100, s100, s22
	s_add_u32 s100, s100, s0
	s_addc_u32 s101, s101, s1
	s_add_u32 s100, s100, 0x18b00000
	s_addc_u32 s101, s101, 0
	global_load_dwordx4 v[144:147], v142, s[100:101]
	s_add_u32 s100, s100, 0x40000
	s_addc_u32 s101, s101, 0
	global_load_dwordx4 v[148:151], v142, s[100:101]
	s_add_u32 s100, s100, 0x40000
	s_addc_u32 s101, s101, 0
	global_load_dwordx4 v[152:155], v142, s[100:101]
	s_add_u32 s100, s100, 0x40000
	s_addc_u32 s101, s101, 0
	global_load_dwordx4 v[156:159], v142, s[100:101]
	s_add_u32 s100, s100, 0x40000
	s_addc_u32 s101, s101, 0
	global_load_dwordx4 v[166:169], v142, s[100:101]
	s_add_u32 s100, s100, 0x40000
	s_addc_u32 s101, s101, 0
	global_load_dwordx4 v[170:173], v142, s[100:101]
	s_add_u32 s100, s100, 0x40000
	s_addc_u32 s101, s101, 0
	global_load_dwordx4 v[174:177], v142, s[100:101]
	s_add_u32 s100, s100, 0x40000
	s_addc_u32 s101, s101, 0
	global_load_dwordx4 v[178:181], v142, s[100:101]
	s_add_u32 s100, s100, 0x40000
	s_addc_u32 s101, s101, 0
	global_load_dwordx4 v[182:185], v142, s[100:101]
	s_add_u32 s100, s100, 0x40000
	s_addc_u32 s101, s101, 0
	global_load_dwordx4 v[186:189], v142, s[100:101]
	s_add_u32 s100, s100, 0x40000
	s_addc_u32 s101, s101, 0
	global_load_dwordx4 v[190:193], v142, s[100:101]
	s_add_u32 s100, s100, 0x40000
	s_addc_u32 s101, s101, 0
	global_load_dwordx4 v[194:197], v142, s[100:101]
	s_add_u32 s100, s100, 0x40000
	s_addc_u32 s101, s101, 0
	global_load_dwordx4 v[198:201], v142, s[100:101]
	s_add_u32 s100, s100, 0x40000
	s_addc_u32 s101, s101, 0
	global_load_dwordx4 v[202:205], v142, s[100:101]
	s_add_u32 s100, s100, 0x40000
	s_addc_u32 s101, s101, 0
	global_load_dwordx4 v[206:209], v142, s[100:101]
	s_add_u32 s100, s100, 0x40000
	s_addc_u32 s101, s101, 0
	global_load_dwordx4 v[210:213], v142, s[100:101]
	s_waitcnt vmcnt(24)
	ds_write_b128 v161, v[32:35]
	ds_write_b128 v161, v[44:47] offset:1088
	ds_write_b128 v161, v[40:43] offset:2176
	ds_write_b128 v161, v[36:39] offset:3264
	ds_write_b128 v161, v[60:63] offset:4352
	ds_write_b128 v161, v[56:59] offset:5440
	ds_write_b128 v161, v[52:55] offset:6528
	ds_write_b128 v161, v[48:51] offset:7616
	ds_write_b128 v161, v[122:125] offset:8704
	ds_write_b128 v161, v[118:121] offset:9792
	ds_write_b128 v161, v[114:117] offset:10880
	ds_write_b128 v161, v[110:113] offset:11968
	ds_write_b128 v161, v[138:141] offset:13056
	ds_write_b128 v161, v[134:137] offset:14144
	ds_write_b128 v161, v[130:133] offset:15232
	ds_write_b128 v161, v[126:129] offset:16320
	ds_read_b128 v[32:35], v164
	ds_read_b128 v[44:47], v164 offset:16
	ds_read_b128 v[40:43], v164 offset:32
	ds_read_b128 v[36:39], v164 offset:48
	ds_read_b128 v[60:63], v164 offset:64
	ds_read_b128 v[56:59], v164 offset:80
	ds_read_b128 v[52:55], v164 offset:96
	ds_read_b128 v[48:51], v164 offset:112
	ds_read_b128 v[122:125], v164 offset:128
	ds_read_b128 v[118:121], v164 offset:144
	ds_read_b128 v[114:117], v164 offset:160
	ds_read_b128 v[110:113], v164 offset:176
	ds_read_b128 v[138:141], v164 offset:192
	ds_read_b128 v[134:137], v164 offset:208
	ds_read_b128 v[130:133], v164 offset:224
	ds_read_b128 v[126:129], v164 offset:240
	s_waitcnt vmcnt(16)
	ds_write_b128 v160, v[28:31]
	ds_write_b128 v160, v[24:27] offset:1152
	ds_write_b128 v160, v[20:23] offset:2304
	ds_write_b128 v160, v[16:19] offset:3456
	ds_write_b128 v160, v[12:15] offset:4608
	ds_write_b128 v160, v[8:11] offset:5760
	ds_write_b128 v160, v[4:7] offset:6912
	ds_write_b128 v160, v[0:3] offset:8064
	ds_read_b128 v[28:31], v67
	ds_read_b128 v[24:27], v67 offset:16
	ds_read_b128 v[20:23], v67 offset:32
	ds_read_b128 v[16:19], v67 offset:48
	ds_read_b128 v[12:15], v67 offset:64
	ds_read_b128 v[8:11], v67 offset:80
	ds_read_b128 v[4:7], v67 offset:96
	ds_read_b128 v[0:3], v67 offset:112
	s_waitcnt lgkmcnt(0)
	s_ashr_i32 s10, s38, 10
	s_ashr_i32 s11, s10, 31
	s_lshl_b64 s[10:11], s[10:11], 24
	s_add_u32 s10, s21, s10
	s_addc_u32 s11, s33, s11
	s_lshl_b32 s23, s23, 16
	s_add_u32 s10, s10, s23
	s_addc_u32 s11, s11, 0
	s_and_b32 s23, s38, 0x300
	s_add_u32 s10, s10, s23
	s_addc_u32 s11, s11, 0
	s_ashr_i32 s39, s38, 31
	s_lshl_b64 s[8:9], s[8:9], 22
	s_or_b32 s8, s8, s22
	s_waitcnt vmcnt(20)
	v_add_f32_e32 v109, v32, v33
	v_add_f32_e32 v108, v34, v109
	v_add_f32_e32 v107, v35, v108
	v_add_f32_e32 v106, v44, v107
	v_add_f32_e32 v105, v45, v106
	v_add_f32_e32 v104, v46, v105
	v_add_f32_e32 v103, v47, v104
	v_add_f32_e32 v102, v40, v103
	v_add_f32_e32 v101, v41, v102
	v_add_f32_e32 v100, v42, v101
	v_add_f32_e32 v99, v43, v100
	v_add_f32_e32 v98, v36, v99
	v_add_f32_e32 v97, v37, v98
	v_add_f32_e32 v96, v38, v97
	v_add_f32_e32 v95, v39, v96
	s_waitcnt vmcnt(16)
	v_add_f32_e32 v94, v60, v95
	v_add_f32_e32 v93, v61, v94
	v_add_f32_e32 v92, v62, v93
	v_add_f32_e32 v91, v63, v92
	v_add_f32_e32 v90, v56, v91
	v_add_f32_e32 v89, v57, v90
	v_add_f32_e32 v88, v58, v89
	v_add_f32_e32 v87, v59, v88
	v_add_f32_e32 v86, v52, v87
	v_add_f32_e32 v85, v53, v86
	v_add_f32_e32 v84, v54, v85
	v_add_f32_e32 v83, v55, v84
	v_add_f32_e32 v82, v48, v83
	v_add_f32_e32 v81, v49, v82
	v_add_f32_e32 v80, v50, v81
	v_add_f32_e32 v77, v51, v80
	s_waitcnt vmcnt(12)
	v_add_f32_e32 v76, v122, v77
	v_add_f32_e32 v75, v123, v76
	v_add_f32_e32 v74, v124, v75
	v_add_f32_e32 v63, v125, v74
	v_add_f32_e32 v62, v118, v63
	v_add_f32_e32 v61, v119, v62
	v_add_f32_e32 v60, v120, v61
	v_add_f32_e32 v59, v121, v60
	v_add_f32_e32 v58, v114, v59
	v_add_f32_e32 v57, v115, v58
	v_add_f32_e32 v56, v116, v57
	v_add_f32_e32 v55, v117, v56
	v_lshl_add_u64 v[34:35], s[10:11], 0, v[72:73]
	global_store_dword v72, v32, s[10:11]
	global_store_dword v72, v109, s[10:11] offset:1024
	global_store_dword v72, v108, s[10:11] offset:2048
	global_store_dword v72, v107, s[10:11] offset:3072
	s_movk_i32 s10, 0x1000
	v_add_f32_e32 v54, v110, v55
	v_add_co_u32_e32 v110, vcc, s10, v34
	v_add_f32_e32 v53, v111, v54
	s_nop 0
	v_addc_co_u32_e32 v111, vcc, 0, v35, vcc
	s_movk_i32 s10, 0x2000
	v_add_f32_e32 v52, v112, v53
	v_add_co_u32_e32 v112, vcc, s10, v34
	v_add_f32_e32 v51, v113, v52
	s_nop 0
	v_addc_co_u32_e32 v113, vcc, 0, v35, vcc
	s_movk_i32 s10, 0x3000
	global_store_dword v[112:113], v106, off offset:-4096
	global_store_dword v[110:111], v105, off offset:1024
	global_store_dword v[110:111], v104, off offset:2048
	global_store_dword v[110:111], v103, off offset:3072
	global_store_dword v[112:113], v102, off
	global_store_dword v[112:113], v101, off offset:1024
	global_store_dword v[112:113], v100, off offset:2048
	global_store_dword v[112:113], v99, off offset:3072
	v_add_co_u32_e32 v110, vcc, s10, v34
	s_movk_i32 s10, 0x4000
	s_nop 0
	v_addc_co_u32_e32 v111, vcc, 0, v35, vcc
	v_add_co_u32_e32 v112, vcc, s10, v34
	s_movk_i32 s10, 0x5000
	s_nop 0
	v_addc_co_u32_e32 v113, vcc, 0, v35, vcc
	global_store_dword v[112:113], v98, off offset:-4096
	global_store_dword v[110:111], v97, off offset:1024
	global_store_dword v[110:111], v96, off offset:2048
	global_store_dword v[110:111], v95, off offset:3072
	global_store_dword v[112:113], v94, off
	global_store_dword v[112:113], v93, off offset:1024
	global_store_dword v[112:113], v92, off offset:2048
	global_store_dword v[112:113], v91, off offset:3072
	v_add_co_u32_e32 v110, vcc, s10, v34
	s_movk_i32 s10, 0x6000
	s_nop 0
	v_addc_co_u32_e32 v111, vcc, 0, v35, vcc
	v_add_co_u32_e32 v112, vcc, s10, v34
	s_movk_i32 s10, 0x7000
	s_nop 0
	v_addc_co_u32_e32 v113, vcc, 0, v35, vcc
	global_store_dword v[112:113], v90, off offset:-4096
	global_store_dword v[110:111], v89, off offset:1024
	global_store_dword v[110:111], v88, off offset:2048
	global_store_dword v[110:111], v87, off offset:3072
	global_store_dword v[112:113], v86, off
	global_store_dword v[112:113], v85, off offset:1024
	global_store_dword v[112:113], v84, off offset:2048
	global_store_dword v[112:113], v83, off offset:3072
	v_add_co_u32_e32 v110, vcc, s10, v34
	s_mov_b32 s10, 0x8000
	s_nop 0
	v_addc_co_u32_e32 v111, vcc, 0, v35, vcc
	s_waitcnt vmcnt(36)
	v_add_f32_e32 v50, v138, v51
	v_add_co_u32_e32 v112, vcc, s10, v34
	v_add_f32_e32 v49, v139, v50
	s_nop 0
	v_addc_co_u32_e32 v113, vcc, 0, v35, vcc
	s_mov_b32 s10, 0x9000
	v_add_f32_e32 v48, v140, v49
	global_store_dword v[112:113], v82, off offset:-4096
	global_store_dword v[110:111], v81, off offset:1024
	global_store_dword v[110:111], v80, off offset:2048
	global_store_dword v[110:111], v77, off offset:3072
	global_store_dword v[112:113], v76, off
	global_store_dword v[112:113], v75, off offset:1024
	global_store_dword v[112:113], v74, off offset:2048
	global_store_dword v[112:113], v63, off offset:3072
	v_add_co_u32_e32 v110, vcc, s10, v34
	v_add_f32_e32 v47, v141, v48
	s_nop 0
	v_addc_co_u32_e32 v111, vcc, 0, v35, vcc
	s_mov_b32 s10, 0xa000
	v_add_f32_e32 v46, v134, v47
	v_add_co_u32_e32 v112, vcc, s10, v34
	v_add_f32_e32 v45, v135, v46
	s_nop 0
	v_addc_co_u32_e32 v113, vcc, 0, v35, vcc
	s_mov_b32 s10, 0xb000
	v_add_f32_e32 v44, v136, v45
	global_store_dword v[112:113], v62, off offset:-4096
	global_store_dword v[110:111], v61, off offset:1024
	global_store_dword v[110:111], v60, off offset:2048
	global_store_dword v[110:111], v59, off offset:3072
	global_store_dword v[112:113], v58, off
	global_store_dword v[112:113], v57, off offset:1024
	global_store_dword v[112:113], v56, off offset:2048
	global_store_dword v[112:113], v55, off offset:3072
	v_add_co_u32_e32 v110, vcc, s10, v34
	v_add_f32_e32 v43, v137, v44
	s_nop 0
	v_addc_co_u32_e32 v111, vcc, 0, v35, vcc
	s_mov_b32 s10, 0xc000
	v_add_f32_e32 v42, v130, v43
	v_add_co_u32_e32 v112, vcc, s10, v34
	v_add_f32_e32 v41, v131, v42
	s_nop 0
	v_addc_co_u32_e32 v113, vcc, 0, v35, vcc
	s_mov_b32 s10, 0xd000
	v_add_f32_e32 v40, v132, v41
	global_store_dword v[112:113], v54, off offset:-4096
	global_store_dword v[110:111], v53, off offset:1024
	global_store_dword v[110:111], v52, off offset:2048
	global_store_dword v[110:111], v51, off offset:3072
	global_store_dword v[112:113], v50, off
	global_store_dword v[112:113], v49, off offset:1024
	global_store_dword v[112:113], v48, off offset:2048
	global_store_dword v[112:113], v47, off offset:3072
	v_add_co_u32_e32 v110, vcc, s10, v34
	v_add_f32_e32 v39, v133, v40
	s_nop 0
	v_addc_co_u32_e32 v111, vcc, 0, v35, vcc
	s_mov_b32 s10, 0xe000
	v_add_f32_e32 v38, v126, v39
	v_add_co_u32_e32 v112, vcc, s10, v34
	v_add_f32_e32 v37, v127, v38
	s_nop 0
	v_addc_co_u32_e32 v113, vcc, 0, v35, vcc
	s_mov_b32 s10, 0xf000
	v_add_f32_e32 v36, v128, v37
	v_add_co_u32_e32 v34, vcc, s10, v34
	v_add_f32_e32 v33, v129, v36
	s_nop 0
	v_addc_co_u32_e32 v35, vcc, 0, v35, vcc
	global_store_dword v[112:113], v46, off offset:-4096
	global_store_dword v[110:111], v45, off offset:1024
	global_store_dword v[110:111], v44, off offset:2048
	global_store_dword v[110:111], v43, off offset:3072
	global_store_dword v[112:113], v42, off
	global_store_dword v[112:113], v41, off offset:1024
	global_store_dword v[112:113], v40, off offset:2048
	global_store_dword v[112:113], v39, off offset:3072
	global_store_dword v[34:35], v38, off
	global_store_dword v[34:35], v37, off offset:1024
	global_store_dword v[34:35], v36, off offset:2048
	global_store_dword v[34:35], v33, off offset:3072
	v_mul_f32_e32 v34, 0x3fb8aa3b, v33
	v_exp_f32_e32 v110, v34
	s_lshl_b64 s[10:11], s[38:39], 8
	v_sub_f32_e32 v32, v33, v32
	v_lshl_add_u64 v[34:35], v[68:69], 0, s[10:11]
	v_mul_f32_e32 v32, 0x3fb8aa3b, v32
	global_store_dword v[34:35], v110, off
	v_exp_f32_e32 v34, v32
	v_sub_f32_e32 v32, v33, v109
	v_mul_f32_e32 v32, 0x3fb8aa3b, v32
	v_exp_f32_e32 v35, v32
	s_waitcnt vmcnt(62)
	v_lshlrev_b32_e32 v110, 16, v28
	v_and_b32_e32 v111, 0xffff0000, v28
	v_sub_f32_e32 v32, v33, v108
	v_pk_mul_f32 v[34:35], v[34:35], v[110:111]
	v_mul_f32_e32 v32, 0x3fb8aa3b, v32
	v_cvt_pk_bf16_f32 v28, v34, v35
	v_exp_f32_e32 v34, v32
	v_sub_f32_e32 v32, v33, v107
	v_mul_f32_e32 v32, 0x3fb8aa3b, v32
	v_exp_f32_e32 v35, v32
	v_lshlrev_b32_e32 v108, 16, v29
	v_and_b32_e32 v109, 0xffff0000, v29
	v_sub_f32_e32 v32, v33, v106
	v_pk_mul_f32 v[34:35], v[34:35], v[108:109]
	v_mul_f32_e32 v32, 0x3fb8aa3b, v32
	v_cvt_pk_bf16_f32 v29, v34, v35
	v_exp_f32_e32 v34, v32
	v_sub_f32_e32 v32, v33, v105
	v_mul_f32_e32 v32, 0x3fb8aa3b, v32
	v_exp_f32_e32 v35, v32
	v_lshlrev_b32_e32 v106, 16, v30
	v_and_b32_e32 v107, 0xffff0000, v30
	v_sub_f32_e32 v32, v33, v104
	v_pk_mul_f32 v[34:35], v[34:35], v[106:107]
	v_mul_f32_e32 v32, 0x3fb8aa3b, v32
	v_cvt_pk_bf16_f32 v30, v34, v35
	v_exp_f32_e32 v34, v32
	v_sub_f32_e32 v32, v33, v103
	v_mul_f32_e32 v32, 0x3fb8aa3b, v32
	v_exp_f32_e32 v35, v32
	v_lshlrev_b32_e32 v104, 16, v31
	v_and_b32_e32 v105, 0xffff0000, v31
	v_pk_mul_f32 v[34:35], v[34:35], v[104:105]
	s_nop 0
	v_cvt_pk_bf16_f32 v31, v34, v35
	ds_write_b128 v67, v[28:31]
	v_sub_f32_e32 v28, v33, v102
	v_sub_f32_e32 v29, v33, v101
	v_mul_f32_e32 v28, 0x3fb8aa3b, v28
	v_mul_f32_e32 v29, 0x3fb8aa3b, v29
	v_exp_f32_e32 v28, v28
	v_exp_f32_e32 v29, v29
	v_lshlrev_b32_e32 v30, 16, v24
	v_and_b32_e32 v31, 0xffff0000, v24
	v_pk_mul_f32 v[28:29], v[28:29], v[30:31]
	s_nop 0
	v_cvt_pk_bf16_f32 v24, v28, v29
	v_sub_f32_e32 v28, v33, v100
	v_sub_f32_e32 v29, v33, v99
	v_mul_f32_e32 v28, 0x3fb8aa3b, v28
	v_mul_f32_e32 v29, 0x3fb8aa3b, v29
	v_exp_f32_e32 v28, v28
	v_exp_f32_e32 v29, v29
	v_lshlrev_b32_e32 v30, 16, v25
	v_and_b32_e32 v31, 0xffff0000, v25
	v_pk_mul_f32 v[28:29], v[28:29], v[30:31]
	s_nop 0
	v_cvt_pk_bf16_f32 v25, v28, v29
	v_sub_f32_e32 v28, v33, v98
	v_sub_f32_e32 v29, v33, v97
	v_mul_f32_e32 v28, 0x3fb8aa3b, v28
	v_mul_f32_e32 v29, 0x3fb8aa3b, v29
	v_exp_f32_e32 v28, v28
	v_exp_f32_e32 v29, v29
	v_lshlrev_b32_e32 v30, 16, v26
	v_and_b32_e32 v31, 0xffff0000, v26
	v_pk_mul_f32 v[28:29], v[28:29], v[30:31]
	s_nop 0
	v_cvt_pk_bf16_f32 v26, v28, v29
	v_sub_f32_e32 v28, v33, v96
	v_sub_f32_e32 v29, v33, v95
	v_mul_f32_e32 v28, 0x3fb8aa3b, v28
	v_mul_f32_e32 v29, 0x3fb8aa3b, v29
	v_exp_f32_e32 v28, v28
	v_exp_f32_e32 v29, v29
	v_lshlrev_b32_e32 v30, 16, v27
	v_and_b32_e32 v31, 0xffff0000, v27
	v_pk_mul_f32 v[28:29], v[28:29], v[30:31]
	s_nop 0
	v_cvt_pk_bf16_f32 v27, v28, v29
	ds_write_b128 v67, v[24:27] offset:16
	v_sub_f32_e32 v24, v33, v94
	v_sub_f32_e32 v25, v33, v93
	v_mul_f32_e32 v24, 0x3fb8aa3b, v24
	v_mul_f32_e32 v25, 0x3fb8aa3b, v25
	v_exp_f32_e32 v24, v24
	v_exp_f32_e32 v25, v25
	v_lshlrev_b32_e32 v26, 16, v20
	v_and_b32_e32 v27, 0xffff0000, v20
	v_pk_mul_f32 v[24:25], v[24:25], v[26:27]
	s_nop 0
	v_cvt_pk_bf16_f32 v20, v24, v25
	v_sub_f32_e32 v24, v33, v92
	v_sub_f32_e32 v25, v33, v91
	v_mul_f32_e32 v24, 0x3fb8aa3b, v24
	v_mul_f32_e32 v25, 0x3fb8aa3b, v25
	v_exp_f32_e32 v24, v24
	v_exp_f32_e32 v25, v25
	v_lshlrev_b32_e32 v26, 16, v21
	v_and_b32_e32 v27, 0xffff0000, v21
	v_pk_mul_f32 v[24:25], v[24:25], v[26:27]
	s_nop 0
	v_cvt_pk_bf16_f32 v21, v24, v25
	v_sub_f32_e32 v24, v33, v90
	v_sub_f32_e32 v25, v33, v89
	v_mul_f32_e32 v24, 0x3fb8aa3b, v24
	v_mul_f32_e32 v25, 0x3fb8aa3b, v25
	v_exp_f32_e32 v24, v24
	v_exp_f32_e32 v25, v25
	v_lshlrev_b32_e32 v26, 16, v22
	v_and_b32_e32 v27, 0xffff0000, v22
	v_pk_mul_f32 v[24:25], v[24:25], v[26:27]
	s_nop 0
	v_cvt_pk_bf16_f32 v22, v24, v25
	v_sub_f32_e32 v24, v33, v88
	v_sub_f32_e32 v25, v33, v87
	v_mul_f32_e32 v24, 0x3fb8aa3b, v24
	v_mul_f32_e32 v25, 0x3fb8aa3b, v25
	v_exp_f32_e32 v24, v24
	v_exp_f32_e32 v25, v25
	v_lshlrev_b32_e32 v26, 16, v23
	v_and_b32_e32 v27, 0xffff0000, v23
	v_pk_mul_f32 v[24:25], v[24:25], v[26:27]
	s_nop 0
	v_cvt_pk_bf16_f32 v23, v24, v25
	ds_write_b128 v67, v[20:23] offset:32
	v_sub_f32_e32 v20, v33, v86
	v_sub_f32_e32 v21, v33, v85
	v_mul_f32_e32 v20, 0x3fb8aa3b, v20
	v_mul_f32_e32 v21, 0x3fb8aa3b, v21
	v_exp_f32_e32 v20, v20
	v_exp_f32_e32 v21, v21
	v_lshlrev_b32_e32 v22, 16, v16
	v_and_b32_e32 v23, 0xffff0000, v16
	v_pk_mul_f32 v[20:21], v[20:21], v[22:23]
	s_nop 0
	v_cvt_pk_bf16_f32 v16, v20, v21
	v_sub_f32_e32 v20, v33, v84
	v_sub_f32_e32 v21, v33, v83
	v_mul_f32_e32 v20, 0x3fb8aa3b, v20
	v_mul_f32_e32 v21, 0x3fb8aa3b, v21
	v_exp_f32_e32 v20, v20
	v_exp_f32_e32 v21, v21
	v_lshlrev_b32_e32 v22, 16, v17
	v_and_b32_e32 v23, 0xffff0000, v17
	v_pk_mul_f32 v[20:21], v[20:21], v[22:23]
	s_nop 0
	v_cvt_pk_bf16_f32 v17, v20, v21
	v_sub_f32_e32 v20, v33, v82
	v_sub_f32_e32 v21, v33, v81
	v_mul_f32_e32 v20, 0x3fb8aa3b, v20
	v_mul_f32_e32 v21, 0x3fb8aa3b, v21
	v_exp_f32_e32 v20, v20
	v_exp_f32_e32 v21, v21
	v_lshlrev_b32_e32 v22, 16, v18
	v_and_b32_e32 v23, 0xffff0000, v18
	v_pk_mul_f32 v[20:21], v[20:21], v[22:23]
	s_nop 0
	v_cvt_pk_bf16_f32 v18, v20, v21
	v_sub_f32_e32 v20, v33, v80
	v_sub_f32_e32 v21, v33, v77
	v_mul_f32_e32 v20, 0x3fb8aa3b, v20
	v_mul_f32_e32 v21, 0x3fb8aa3b, v21
	v_exp_f32_e32 v20, v20
	v_exp_f32_e32 v21, v21
	v_lshlrev_b32_e32 v22, 16, v19
	v_and_b32_e32 v23, 0xffff0000, v19
	v_pk_mul_f32 v[20:21], v[20:21], v[22:23]
	s_nop 0
	v_cvt_pk_bf16_f32 v19, v20, v21
	ds_write_b128 v67, v[16:19] offset:48
	v_sub_f32_e32 v16, v33, v76
	v_sub_f32_e32 v17, v33, v75
	v_mul_f32_e32 v16, 0x3fb8aa3b, v16
	v_mul_f32_e32 v17, 0x3fb8aa3b, v17
	v_exp_f32_e32 v16, v16
	v_exp_f32_e32 v17, v17
	v_lshlrev_b32_e32 v18, 16, v12
	v_and_b32_e32 v19, 0xffff0000, v12
	v_mov_b64_e32 v[76:77], v[70:71]
	v_pk_mul_f32 v[16:17], v[16:17], v[18:19]
	v_lshlrev_b32_e32 v18, 16, v13
	v_cvt_pk_bf16_f32 v12, v16, v17
	v_sub_f32_e32 v16, v33, v74
	v_sub_f32_e32 v17, v33, v63
	v_mul_f32_e32 v16, 0x3fb8aa3b, v16
	v_mul_f32_e32 v17, 0x3fb8aa3b, v17
	v_exp_f32_e32 v16, v16
	v_exp_f32_e32 v17, v17
	v_and_b32_e32 v19, 0xffff0000, v13
	v_lshl_add_u64 v[74:75], s[8:9], 0, v[64:65]
	s_mov_b32 s8, 4
	v_pk_mul_f32 v[16:17], v[16:17], v[18:19]
	v_lshlrev_b32_e32 v18, 16, v14
	v_cvt_pk_bf16_f32 v13, v16, v17
	v_sub_f32_e32 v16, v33, v62
	v_sub_f32_e32 v17, v33, v61
	v_mul_f32_e32 v16, 0x3fb8aa3b, v16
	v_mul_f32_e32 v17, 0x3fb8aa3b, v17
	v_exp_f32_e32 v16, v16
	v_exp_f32_e32 v17, v17
	v_and_b32_e32 v19, 0xffff0000, v14
	v_pk_mul_f32 v[16:17], v[16:17], v[18:19]
	s_nop 0
	v_cvt_pk_bf16_f32 v14, v16, v17
	v_sub_f32_e32 v16, v33, v60
	v_sub_f32_e32 v17, v33, v59
	v_mul_f32_e32 v16, 0x3fb8aa3b, v16
	v_mul_f32_e32 v17, 0x3fb8aa3b, v17
	v_exp_f32_e32 v16, v16
	v_exp_f32_e32 v17, v17
	v_lshlrev_b32_e32 v18, 16, v15
	v_and_b32_e32 v19, 0xffff0000, v15
	v_pk_mul_f32 v[16:17], v[16:17], v[18:19]
	s_nop 0
	v_cvt_pk_bf16_f32 v15, v16, v17
	ds_write_b128 v67, v[12:15] offset:64
	v_sub_f32_e32 v12, v33, v58
	v_sub_f32_e32 v13, v33, v57
	v_mul_f32_e32 v12, 0x3fb8aa3b, v12
	v_mul_f32_e32 v13, 0x3fb8aa3b, v13
	v_exp_f32_e32 v12, v12
	v_exp_f32_e32 v13, v13
	v_lshlrev_b32_e32 v14, 16, v8
	v_and_b32_e32 v15, 0xffff0000, v8
	v_pk_mul_f32 v[12:13], v[12:13], v[14:15]
	s_nop 0
	v_cvt_pk_bf16_f32 v8, v12, v13
	v_sub_f32_e32 v12, v33, v56
	v_sub_f32_e32 v13, v33, v55
	v_mul_f32_e32 v12, 0x3fb8aa3b, v12
	v_mul_f32_e32 v13, 0x3fb8aa3b, v13
	v_exp_f32_e32 v12, v12
	v_exp_f32_e32 v13, v13
	v_lshlrev_b32_e32 v14, 16, v9
	v_and_b32_e32 v15, 0xffff0000, v9
	v_pk_mul_f32 v[12:13], v[12:13], v[14:15]
	s_nop 0
	v_cvt_pk_bf16_f32 v9, v12, v13
	v_sub_f32_e32 v12, v33, v54
	v_sub_f32_e32 v13, v33, v53
	v_mul_f32_e32 v12, 0x3fb8aa3b, v12
	v_mul_f32_e32 v13, 0x3fb8aa3b, v13
	v_exp_f32_e32 v12, v12
	v_exp_f32_e32 v13, v13
	v_lshlrev_b32_e32 v14, 16, v10
	v_and_b32_e32 v15, 0xffff0000, v10
	v_pk_mul_f32 v[12:13], v[12:13], v[14:15]
	s_nop 0
	v_cvt_pk_bf16_f32 v10, v12, v13
	v_sub_f32_e32 v12, v33, v52
	v_sub_f32_e32 v13, v33, v51
	v_mul_f32_e32 v12, 0x3fb8aa3b, v12
	v_mul_f32_e32 v13, 0x3fb8aa3b, v13
	v_exp_f32_e32 v12, v12
	v_exp_f32_e32 v13, v13
	v_lshlrev_b32_e32 v14, 16, v11
	v_and_b32_e32 v15, 0xffff0000, v11
	v_pk_mul_f32 v[12:13], v[12:13], v[14:15]
	s_nop 0
	v_cvt_pk_bf16_f32 v11, v12, v13
	ds_write_b128 v67, v[8:11] offset:80
	v_sub_f32_e32 v8, v33, v50
	v_sub_f32_e32 v9, v33, v49
	v_mul_f32_e32 v8, 0x3fb8aa3b, v8
	v_mul_f32_e32 v9, 0x3fb8aa3b, v9
	v_exp_f32_e32 v8, v8
	v_exp_f32_e32 v9, v9
	v_lshlrev_b32_e32 v10, 16, v4
	v_and_b32_e32 v11, 0xffff0000, v4
	v_pk_mul_f32 v[8:9], v[8:9], v[10:11]
	s_nop 0
	v_cvt_pk_bf16_f32 v4, v8, v9
	v_sub_f32_e32 v8, v33, v48
	v_sub_f32_e32 v9, v33, v47
	v_mul_f32_e32 v8, 0x3fb8aa3b, v8
	v_mul_f32_e32 v9, 0x3fb8aa3b, v9
	v_exp_f32_e32 v8, v8
	v_exp_f32_e32 v9, v9
	v_lshlrev_b32_e32 v10, 16, v5
	v_and_b32_e32 v11, 0xffff0000, v5
	v_pk_mul_f32 v[8:9], v[8:9], v[10:11]
	s_nop 0
	v_cvt_pk_bf16_f32 v5, v8, v9
	v_sub_f32_e32 v8, v33, v46
	v_sub_f32_e32 v9, v33, v45
	v_mul_f32_e32 v8, 0x3fb8aa3b, v8
	v_mul_f32_e32 v9, 0x3fb8aa3b, v9
	v_exp_f32_e32 v8, v8
	v_exp_f32_e32 v9, v9
	v_lshlrev_b32_e32 v10, 16, v6
	v_and_b32_e32 v11, 0xffff0000, v6
	v_pk_mul_f32 v[8:9], v[8:9], v[10:11]
	s_nop 0
	v_cvt_pk_bf16_f32 v6, v8, v9
	v_sub_f32_e32 v8, v33, v44
	v_sub_f32_e32 v9, v33, v43
	v_mul_f32_e32 v8, 0x3fb8aa3b, v8
	v_mul_f32_e32 v9, 0x3fb8aa3b, v9
	v_exp_f32_e32 v8, v8
	v_exp_f32_e32 v9, v9
	v_lshlrev_b32_e32 v10, 16, v7
	v_and_b32_e32 v11, 0xffff0000, v7
	v_pk_mul_f32 v[8:9], v[8:9], v[10:11]
	s_nop 0
	v_cvt_pk_bf16_f32 v7, v8, v9
	ds_write_b128 v67, v[4:7] offset:96
	v_sub_f32_e32 v4, v33, v42
	v_sub_f32_e32 v5, v33, v41
	v_mul_f32_e32 v4, 0x3fb8aa3b, v4
	v_mul_f32_e32 v5, 0x3fb8aa3b, v5
	v_exp_f32_e32 v4, v4
	v_exp_f32_e32 v5, v5
	v_lshlrev_b32_e32 v6, 16, v0
	v_and_b32_e32 v7, 0xffff0000, v0
	v_pk_mul_f32 v[4:5], v[4:5], v[6:7]
	s_nop 0
	v_cvt_pk_bf16_f32 v0, v4, v5
	v_sub_f32_e32 v4, v33, v40
	v_sub_f32_e32 v5, v33, v39
	v_mul_f32_e32 v4, 0x3fb8aa3b, v4
	v_mul_f32_e32 v5, 0x3fb8aa3b, v5
	v_exp_f32_e32 v4, v4
	v_exp_f32_e32 v5, v5
	v_lshlrev_b32_e32 v6, 16, v1
	v_and_b32_e32 v7, 0xffff0000, v1
	v_pk_mul_f32 v[4:5], v[4:5], v[6:7]
	s_nop 0
	v_cvt_pk_bf16_f32 v1, v4, v5
	v_sub_f32_e32 v4, v33, v38
	v_sub_f32_e32 v5, v33, v37
	v_mul_f32_e32 v4, 0x3fb8aa3b, v4
	v_mul_f32_e32 v5, 0x3fb8aa3b, v5
	v_exp_f32_e32 v4, v4
	v_exp_f32_e32 v5, v5
	v_lshlrev_b32_e32 v6, 16, v2
	v_and_b32_e32 v7, 0xffff0000, v2
	v_pk_mul_f32 v[4:5], v[4:5], v[6:7]
	s_nop 0
	v_cvt_pk_bf16_f32 v2, v4, v5
	v_sub_f32_e32 v4, v33, v36
	v_sub_f32_e32 v5, v33, v33
	v_mul_f32_e32 v4, 0x3fb8aa3b, v4
	v_mul_f32_e32 v5, 0x3fb8aa3b, v5
	v_exp_f32_e32 v4, v4
	v_exp_f32_e32 v5, v5
	v_lshlrev_b32_e32 v6, 16, v3
	v_and_b32_e32 v7, 0xffff0000, v3
	v_pk_mul_f32 v[4:5], v[4:5], v[6:7]
	s_nop 0
	v_cvt_pk_bf16_f32 v3, v4, v5
	ds_write_b128 v67, v[0:3] offset:112
	ds_read_b128 v[32:35], v78
	ds_read_b128 v[36:39], v78 offset:32
	ds_read_b128 v[40:43], v79
	ds_read_b128 v[44:47], v79 offset:32
	ds_read_b128 v[48:51], v78 offset:64
	ds_read_b128 v[52:55], v79 offset:64
	ds_read_b128 v[56:59], v78 offset:96
	ds_read_b128 v[60:63], v79 offset:96
	s_mov_b32 s9, 0xb800000
	s_mov_b64 s[10:11], 0x2000
	s_waitcnt vmcnt(63)
	ds_write_b128 v160, v[144:147] offset:9216
	ds_write_b128 v160, v[148:151] offset:10368
	ds_write_b128 v160, v[152:155] offset:11520
	ds_write_b128 v160, v[156:159] offset:12672
	ds_read_b128 v[144:147], v165
	ds_read_b128 v[148:151], v165 offset:32
	ds_read_b128 v[152:155], v165 offset:64
	ds_read_b128 v[156:159], v165 offset:96
	s_waitcnt lgkmcnt(0)
	v_mfma_f32_32x32x16_bf16 v[0:15], v[144:147], v[32:35], 0
	v_mfma_f32_32x32x16_bf16 v[16:31], v[144:147], v[40:43], 0
	v_mfma_f32_32x32x16_bf16 v[0:15], v[148:151], v[36:39], v[0:15]
	v_mfma_f32_32x32x16_bf16 v[16:31], v[148:151], v[44:47], v[16:31]
	v_mfma_f32_32x32x16_bf16 v[0:15], v[152:155], v[48:51], v[0:15]
	v_mfma_f32_32x32x16_bf16 v[16:31], v[152:155], v[52:55], v[16:31]
	v_mfma_f32_32x32x16_bf16 v[0:15], v[156:159], v[56:59], v[0:15]
	v_mfma_f32_32x32x16_bf16 v[16:31], v[156:159], v[60:63], v[16:31]
	v_lshl_add_u64 v[80:81], s[0:1], 0, v[76:77]
	v_add_co_u32_e32 v82, vcc, s9, v80
	s_mov_b32 s9, 0xb801000
	s_nop 0
	v_addc_co_u32_e32 v83, vcc, 0, v81, vcc
	v_add_co_u32_e32 v80, vcc, s9, v80
	v_lshl_add_u64 v[76:77], v[76:77], 0, s[10:11]
	s_nop 0
	v_addc_co_u32_e32 v81, vcc, 0, v81, vcc
	s_nop 0
	global_store_dword v[80:81], v0, off offset:-4096
	s_nop 0
	global_store_dword v[82:83], v16, off offset:128
	global_store_dword v[82:83], v1, off offset:256
	global_store_dword v[82:83], v17, off offset:384
	global_store_dword v[82:83], v2, off offset:512
	global_store_dword v[82:83], v18, off offset:640
	global_store_dword v[82:83], v3, off offset:768
	global_store_dword v[82:83], v19, off offset:896
	global_store_dword v[82:83], v4, off offset:2048
	global_store_dword v[82:83], v20, off offset:2176
	global_store_dword v[82:83], v5, off offset:2304
	global_store_dword v[82:83], v21, off offset:2432
	global_store_dword v[82:83], v6, off offset:2560
	global_store_dword v[82:83], v22, off offset:2688
	global_store_dword v[82:83], v7, off offset:2816
	global_store_dword v[82:83], v23, off offset:2944
	global_store_dword v[80:81], v8, off
	global_store_dword v[80:81], v24, off offset:128
	global_store_dword v[80:81], v9, off offset:256
	global_store_dword v[80:81], v25, off offset:384
	global_store_dword v[80:81], v10, off offset:512
	global_store_dword v[80:81], v26, off offset:640
	global_store_dword v[80:81], v11, off offset:768
	global_store_dword v[80:81], v27, off offset:896
	global_store_dword v[80:81], v12, off offset:2048
	global_store_dword v[80:81], v28, off offset:2176
	global_store_dword v[80:81], v13, off offset:2304
	global_store_dword v[80:81], v29, off offset:2432
	global_store_dword v[80:81], v14, off offset:2560
	global_store_dword v[80:81], v30, off offset:2688
	global_store_dword v[80:81], v15, off offset:2816
	global_store_dword v[80:81], v31, off offset:2944
	s_mov_b32 s9, 0xb800000
	s_mov_b64 s[10:11], 0x2000
	ds_write_b128 v160, v[166:169] offset:9216
	ds_write_b128 v160, v[170:173] offset:10368
	ds_write_b128 v160, v[174:177] offset:11520
	ds_write_b128 v160, v[178:181] offset:12672
	ds_read_b128 v[144:147], v165
	ds_read_b128 v[148:151], v165 offset:32
	ds_read_b128 v[152:155], v165 offset:64
	ds_read_b128 v[156:159], v165 offset:96
	s_waitcnt lgkmcnt(0)
	v_mfma_f32_32x32x16_bf16 v[0:15], v[144:147], v[32:35], 0
	v_mfma_f32_32x32x16_bf16 v[16:31], v[144:147], v[40:43], 0
	v_mfma_f32_32x32x16_bf16 v[0:15], v[148:151], v[36:39], v[0:15]
	v_mfma_f32_32x32x16_bf16 v[16:31], v[148:151], v[44:47], v[16:31]
	v_mfma_f32_32x32x16_bf16 v[0:15], v[152:155], v[48:51], v[0:15]
	v_mfma_f32_32x32x16_bf16 v[16:31], v[152:155], v[52:55], v[16:31]
	v_mfma_f32_32x32x16_bf16 v[0:15], v[156:159], v[56:59], v[0:15]
	v_mfma_f32_32x32x16_bf16 v[16:31], v[156:159], v[60:63], v[16:31]
	v_lshl_add_u64 v[80:81], s[0:1], 0, v[76:77]
	v_add_co_u32_e32 v82, vcc, s9, v80
	s_mov_b32 s9, 0xb801000
	s_nop 0
	v_addc_co_u32_e32 v83, vcc, 0, v81, vcc
	v_add_co_u32_e32 v80, vcc, s9, v80
	v_lshl_add_u64 v[76:77], v[76:77], 0, s[10:11]
	s_nop 0
	v_addc_co_u32_e32 v81, vcc, 0, v81, vcc
	s_nop 0
	global_store_dword v[80:81], v0, off offset:-4096
	s_nop 0
	global_store_dword v[82:83], v16, off offset:128
	global_store_dword v[82:83], v1, off offset:256
	global_store_dword v[82:83], v17, off offset:384
	global_store_dword v[82:83], v2, off offset:512
	global_store_dword v[82:83], v18, off offset:640
	global_store_dword v[82:83], v3, off offset:768
	global_store_dword v[82:83], v19, off offset:896
	global_store_dword v[82:83], v4, off offset:2048
	global_store_dword v[82:83], v20, off offset:2176
	global_store_dword v[82:83], v5, off offset:2304
	global_store_dword v[82:83], v21, off offset:2432
	global_store_dword v[82:83], v6, off offset:2560
	global_store_dword v[82:83], v22, off offset:2688
	global_store_dword v[82:83], v7, off offset:2816
	global_store_dword v[82:83], v23, off offset:2944
	global_store_dword v[80:81], v8, off
	global_store_dword v[80:81], v24, off offset:128
	global_store_dword v[80:81], v9, off offset:256
	global_store_dword v[80:81], v25, off offset:384
	global_store_dword v[80:81], v10, off offset:512
	global_store_dword v[80:81], v26, off offset:640
	global_store_dword v[80:81], v11, off offset:768
	global_store_dword v[80:81], v27, off offset:896
	global_store_dword v[80:81], v12, off offset:2048
	global_store_dword v[80:81], v28, off offset:2176
	global_store_dword v[80:81], v13, off offset:2304
	global_store_dword v[80:81], v29, off offset:2432
	global_store_dword v[80:81], v14, off offset:2560
	global_store_dword v[80:81], v30, off offset:2688
	global_store_dword v[80:81], v15, off offset:2816
	global_store_dword v[80:81], v31, off offset:2944
	s_mov_b32 s9, 0xb800000
	s_mov_b64 s[10:11], 0x2000
	ds_write_b128 v160, v[182:185] offset:9216
	ds_write_b128 v160, v[186:189] offset:10368
	ds_write_b128 v160, v[190:193] offset:11520
	ds_write_b128 v160, v[194:197] offset:12672
	ds_read_b128 v[144:147], v165
	ds_read_b128 v[148:151], v165 offset:32
	ds_read_b128 v[152:155], v165 offset:64
	ds_read_b128 v[156:159], v165 offset:96
	s_waitcnt lgkmcnt(0)
	v_mfma_f32_32x32x16_bf16 v[0:15], v[144:147], v[32:35], 0
	v_mfma_f32_32x32x16_bf16 v[16:31], v[144:147], v[40:43], 0
	v_mfma_f32_32x32x16_bf16 v[0:15], v[148:151], v[36:39], v[0:15]
	v_mfma_f32_32x32x16_bf16 v[16:31], v[148:151], v[44:47], v[16:31]
	v_mfma_f32_32x32x16_bf16 v[0:15], v[152:155], v[48:51], v[0:15]
	v_mfma_f32_32x32x16_bf16 v[16:31], v[152:155], v[52:55], v[16:31]
	v_mfma_f32_32x32x16_bf16 v[0:15], v[156:159], v[56:59], v[0:15]
	v_mfma_f32_32x32x16_bf16 v[16:31], v[156:159], v[60:63], v[16:31]
	v_lshl_add_u64 v[80:81], s[0:1], 0, v[76:77]
	v_add_co_u32_e32 v82, vcc, s9, v80
	s_mov_b32 s9, 0xb801000
	s_nop 0
	v_addc_co_u32_e32 v83, vcc, 0, v81, vcc
	v_add_co_u32_e32 v80, vcc, s9, v80
	v_lshl_add_u64 v[76:77], v[76:77], 0, s[10:11]
	s_nop 0
	v_addc_co_u32_e32 v81, vcc, 0, v81, vcc
	s_nop 0
	global_store_dword v[80:81], v0, off offset:-4096
	s_nop 0
	global_store_dword v[82:83], v16, off offset:128
	global_store_dword v[82:83], v1, off offset:256
	global_store_dword v[82:83], v17, off offset:384
	global_store_dword v[82:83], v2, off offset:512
	global_store_dword v[82:83], v18, off offset:640
	global_store_dword v[82:83], v3, off offset:768
	global_store_dword v[82:83], v19, off offset:896
	global_store_dword v[82:83], v4, off offset:2048
	global_store_dword v[82:83], v20, off offset:2176
	global_store_dword v[82:83], v5, off offset:2304
	global_store_dword v[82:83], v21, off offset:2432
	global_store_dword v[82:83], v6, off offset:2560
	global_store_dword v[82:83], v22, off offset:2688
	global_store_dword v[82:83], v7, off offset:2816
	global_store_dword v[82:83], v23, off offset:2944
	global_store_dword v[80:81], v8, off
	global_store_dword v[80:81], v24, off offset:128
	global_store_dword v[80:81], v9, off offset:256
	global_store_dword v[80:81], v25, off offset:384
	global_store_dword v[80:81], v10, off offset:512
	global_store_dword v[80:81], v26, off offset:640
	global_store_dword v[80:81], v11, off offset:768
	global_store_dword v[80:81], v27, off offset:896
	global_store_dword v[80:81], v12, off offset:2048
	global_store_dword v[80:81], v28, off offset:2176
	global_store_dword v[80:81], v13, off offset:2304
	global_store_dword v[80:81], v29, off offset:2432
	global_store_dword v[80:81], v14, off offset:2560
	global_store_dword v[80:81], v30, off offset:2688
	global_store_dword v[80:81], v15, off offset:2816
	global_store_dword v[80:81], v31, off offset:2944
	s_mov_b32 s9, 0xb800000
	s_mov_b64 s[10:11], 0x2000
	ds_write_b128 v160, v[198:201] offset:9216
	ds_write_b128 v160, v[202:205] offset:10368
	ds_write_b128 v160, v[206:209] offset:11520
	ds_write_b128 v160, v[210:213] offset:12672
	ds_read_b128 v[144:147], v165
	ds_read_b128 v[148:151], v165 offset:32
	ds_read_b128 v[152:155], v165 offset:64
	ds_read_b128 v[156:159], v165 offset:96
	s_waitcnt lgkmcnt(0)
	v_mfma_f32_32x32x16_bf16 v[0:15], v[144:147], v[32:35], 0
	v_mfma_f32_32x32x16_bf16 v[16:31], v[144:147], v[40:43], 0
	v_mfma_f32_32x32x16_bf16 v[0:15], v[148:151], v[36:39], v[0:15]
	v_mfma_f32_32x32x16_bf16 v[16:31], v[148:151], v[44:47], v[16:31]
	v_mfma_f32_32x32x16_bf16 v[0:15], v[152:155], v[48:51], v[0:15]
	v_mfma_f32_32x32x16_bf16 v[16:31], v[152:155], v[52:55], v[16:31]
	v_mfma_f32_32x32x16_bf16 v[0:15], v[156:159], v[56:59], v[0:15]
	v_mfma_f32_32x32x16_bf16 v[16:31], v[156:159], v[60:63], v[16:31]
	v_lshl_add_u64 v[80:81], s[0:1], 0, v[76:77]
	v_add_co_u32_e32 v82, vcc, s9, v80
	s_mov_b32 s9, 0xb801000
	s_nop 0
	v_addc_co_u32_e32 v83, vcc, 0, v81, vcc
	v_add_co_u32_e32 v80, vcc, s9, v80
	v_lshl_add_u64 v[76:77], v[76:77], 0, s[10:11]
	s_nop 0
	v_addc_co_u32_e32 v81, vcc, 0, v81, vcc
	s_nop 0
	global_store_dword v[80:81], v0, off offset:-4096
	s_nop 0
	global_store_dword v[82:83], v16, off offset:128
	global_store_dword v[82:83], v1, off offset:256
	global_store_dword v[82:83], v17, off offset:384
	global_store_dword v[82:83], v2, off offset:512
	global_store_dword v[82:83], v18, off offset:640
	global_store_dword v[82:83], v3, off offset:768
	global_store_dword v[82:83], v19, off offset:896
	global_store_dword v[82:83], v4, off offset:2048
	global_store_dword v[82:83], v20, off offset:2176
	global_store_dword v[82:83], v5, off offset:2304
	global_store_dword v[82:83], v21, off offset:2432
	global_store_dword v[82:83], v6, off offset:2560
	global_store_dword v[82:83], v22, off offset:2688
	global_store_dword v[82:83], v7, off offset:2816
	global_store_dword v[82:83], v23, off offset:2944
	global_store_dword v[80:81], v8, off
	global_store_dword v[80:81], v24, off offset:128
	global_store_dword v[80:81], v9, off offset:256
	global_store_dword v[80:81], v25, off offset:384
	global_store_dword v[80:81], v10, off offset:512
	global_store_dword v[80:81], v26, off offset:640
	global_store_dword v[80:81], v11, off offset:768
	global_store_dword v[80:81], v27, off offset:896
	global_store_dword v[80:81], v12, off offset:2048
	global_store_dword v[80:81], v28, off offset:2176
	global_store_dword v[80:81], v13, off offset:2304
	global_store_dword v[80:81], v29, off offset:2432
	global_store_dword v[80:81], v14, off offset:2560
	global_store_dword v[80:81], v30, off offset:2688
	global_store_dword v[80:81], v15, off offset:2816
	global_store_dword v[80:81], v31, off offset:2944
	s_add_i32 s38, s38, s92
	s_add_i32 s20, s20, s92
	s_cmpk_gt_i32 s38, 0x7ff
	v_lshl_add_u64 v[70:71], v[70:71], 0, s[46:47]
	s_cbranch_scc0 .LBB0_701
